# P4->P5 grid barrier replaced by a 4-workgroup row-panel hand-off (panel counter + grid-wide arrival counters for the cross-panel hazards)
# speedup vs baseline: 1.0150x; 1.0055x over previous
; #define LAS __attribute__((address_space(3)))
; __device__ __forceinline__ unsigned xb_xcc_id() { return (unsigned)__builtin_amdgcn_s_getreg((3 << 11) | 20) & 0xFu; }
; __global__ void __launch_bounds__(512, 2) hymba_fwd(Params p) {
;     extern __shared__ __attribute__((aligned(16))) unsigned char shm[];
;     LAS unsigned char* lds = (LAS unsigned char*)shm;
;     cg::grid_group grid = cg::this_grid();
;     unsigned char* ws = p.ws;
;     const int G = gridDim.x, c = blockIdx.x;
;     XB xb; xb.bar = (unsigned*)(ws + OFF_BAR); xb.x = xb_xcc_id();
;     if (c == 0) for (int i = threadIdx.x; i < 2176; i += 512) xb.bar[1024 + i] = 0u;
;     if (threadIdx.x == 0) xb.bar[3200 + c] = xb.x;
_Z9hymba_fwd6Params:
	s_load_dwordx2 s[82:83], s[0:1], 0x100
	s_load_dword s33, s[0:1], 0x108
	s_add_u32 s24, s0, 0x108
	s_addc_u32 s25, s1, 0
	s_getreg_b32 s3, hwreg(HW_REG_XCC_ID, 0, 4)
	s_waitcnt lgkmcnt(0)
	s_add_u32 s4, s82, 0x1b6e900
	s_addc_u32 s5, s83, 0
	s_cmp_eq_u32 s2, 0
	v_writelane_b32 v253, s4, 0
	s_mov_b32 s8, 0
	s_cselect_b64 s[6:7], -1, 0
	s_cmp_lg_u32 s2, 0
	v_and_b32_e32 v132, 0x3ff, v0
	v_writelane_b32 v253, s5, 1
	s_cbranch_scc1 .LBB0_8
	v_cmp_eq_u32_e32 vcc, 0, v132
	s_and_saveexec_b64 s[98:99], vcc
	s_cbranch_execz .Lgs_init_done
	s_load_dwordx2 s[100:101], s[24:25], 0x58
	v_mov_b32_e32 v1, 0
	v_mov_b32_e32 v2, 0x3600
	global_store_dword v2, v1, s[4:5] offset:0 sc0 sc1
	global_store_dword v2, v1, s[4:5] offset:128 sc0 sc1
	global_store_dword v2, v1, s[4:5] offset:256 sc0 sc1
	global_store_dword v2, v1, s[4:5] offset:384 sc0 sc1
	global_store_dword v2, v1, s[4:5] offset:512 sc0 sc1
	global_store_dword v2, v1, s[4:5] offset:640 sc0 sc1
	global_store_dword v2, v1, s[4:5] offset:768 sc0 sc1
	global_store_dword v2, v1, s[4:5] offset:896 sc0 sc1
	global_store_dword v2, v1, s[4:5] offset:1024 sc0 sc1
	global_store_dword v2, v1, s[4:5] offset:1152 sc0 sc1
	global_store_dword v2, v1, s[4:5] offset:1280 sc0 sc1
	global_store_dword v2, v1, s[4:5] offset:1408 sc0 sc1
	global_store_dword v2, v1, s[4:5] offset:1536 sc0 sc1
	global_store_dword v2, v1, s[4:5] offset:1664 sc0 sc1
	global_store_dword v2, v1, s[4:5] offset:1792 sc0 sc1
	global_store_dword v2, v1, s[4:5] offset:1920 sc0 sc1
	global_store_dword v2, v1, s[4:5] offset:2048 sc0 sc1
	v_mov_b32_e32 v4, 0
	v_mov_b32_e32 v5, 0
	v_mov_b32_e32 v6, 0
	v_mov_b32_e32 v7, 0
	global_store_dwordx4 v1, v[4:7], s[4:5] offset:0 sc0 sc1
	global_store_dwordx4 v1, v[4:7], s[4:5] offset:64 sc0 sc1
	global_store_dwordx4 v1, v[4:7], s[4:5] offset:128 sc0 sc1
	global_store_dwordx4 v1, v[4:7], s[4:5] offset:192 sc0 sc1
	global_store_dwordx4 v1, v[4:7], s[4:5] offset:256 sc0 sc1
	global_store_dwordx4 v1, v[4:7], s[4:5] offset:320 sc0 sc1
	global_store_dwordx4 v1, v[4:7], s[4:5] offset:384 sc0 sc1
	global_store_dwordx4 v1, v[4:7], s[4:5] offset:448 sc0 sc1
	global_store_dwordx4 v1, v[4:7], s[4:5] offset:512 sc0 sc1
	global_store_dwordx4 v1, v[4:7], s[4:5] offset:576 sc0 sc1
	global_store_dwordx4 v1, v[4:7], s[4:5] offset:640 sc0 sc1
	global_store_dwordx4 v1, v[4:7], s[4:5] offset:704 sc0 sc1
	global_store_dwordx4 v1, v[4:7], s[4:5] offset:768 sc0 sc1
	global_store_dwordx4 v1, v[4:7], s[4:5] offset:832 sc0 sc1
	global_store_dwordx4 v1, v[4:7], s[4:5] offset:896 sc0 sc1
	global_store_dwordx4 v1, v[4:7], s[4:5] offset:960 sc0 sc1
	global_store_dwordx4 v1, v[4:7], s[4:5] offset:1024 sc0 sc1
	global_store_dwordx4 v1, v[4:7], s[4:5] offset:1088 sc0 sc1
	global_store_dwordx4 v1, v[4:7], s[4:5] offset:1152 sc0 sc1
	global_store_dwordx4 v1, v[4:7], s[4:5] offset:1216 sc0 sc1
	global_store_dwordx4 v1, v[4:7], s[4:5] offset:1280 sc0 sc1
	global_store_dwordx4 v1, v[4:7], s[4:5] offset:1344 sc0 sc1
	global_store_dwordx4 v1, v[4:7], s[4:5] offset:1408 sc0 sc1
	global_store_dwordx4 v1, v[4:7], s[4:5] offset:1472 sc0 sc1
	global_store_dwordx4 v1, v[4:7], s[4:5] offset:1536 sc0 sc1
	global_store_dwordx4 v1, v[4:7], s[4:5] offset:1600 sc0 sc1
	global_store_dwordx4 v1, v[4:7], s[4:5] offset:1664 sc0 sc1
	global_store_dwordx4 v1, v[4:7], s[4:5] offset:1728 sc0 sc1
	global_store_dwordx4 v1, v[4:7], s[4:5] offset:1792 sc0 sc1
	global_store_dwordx4 v1, v[4:7], s[4:5] offset:1856 sc0 sc1
	global_store_dwordx4 v1, v[4:7], s[4:5] offset:1920 sc0 sc1
	global_store_dwordx4 v1, v[4:7], s[4:5] offset:1984 sc0 sc1
	global_store_dwordx4 v1, v[4:7], s[4:5] offset:2048 sc0 sc1
	global_store_dwordx4 v1, v[4:7], s[4:5] offset:2112 sc0 sc1
	global_store_dwordx4 v1, v[4:7], s[4:5] offset:2176 sc0 sc1
	global_store_dwordx4 v1, v[4:7], s[4:5] offset:2240 sc0 sc1
	global_store_dwordx4 v1, v[4:7], s[4:5] offset:2304 sc0 sc1
	global_store_dwordx4 v1, v[4:7], s[4:5] offset:2368 sc0 sc1
	global_store_dwordx4 v1, v[4:7], s[4:5] offset:2432 sc0 sc1
	global_store_dwordx4 v1, v[4:7], s[4:5] offset:2496 sc0 sc1
	global_store_dwordx4 v1, v[4:7], s[4:5] offset:2560 sc0 sc1
	global_store_dwordx4 v1, v[4:7], s[4:5] offset:2624 sc0 sc1
	global_store_dwordx4 v1, v[4:7], s[4:5] offset:2688 sc0 sc1
	global_store_dwordx4 v1, v[4:7], s[4:5] offset:2752 sc0 sc1
	global_store_dwordx4 v1, v[4:7], s[4:5] offset:2816 sc0 sc1
	global_store_dwordx4 v1, v[4:7], s[4:5] offset:2880 sc0 sc1
	global_store_dwordx4 v1, v[4:7], s[4:5] offset:2944 sc0 sc1
	global_store_dwordx4 v1, v[4:7], s[4:5] offset:3008 sc0 sc1
	global_store_dwordx4 v1, v[4:7], s[4:5] offset:3072 sc0 sc1
	global_store_dwordx4 v1, v[4:7], s[4:5] offset:3136 sc0 sc1
; __global__ void __launch_bounds__(512, 2) hymba_fwd(Params p) {
;     ...
;     if (c == 0) for (int i = threadIdx.x; i < 2176; i += 512) xb.bar[1024 + i] = 0u;
;     if (threadIdx.x == 0) xb.bar[3200 + c] = xb.x;
	global_store_dwordx4 v1, v[4:7], s[4:5] offset:3200 sc0 sc1
	global_store_dwordx4 v1, v[4:7], s[4:5] offset:3264 sc0 sc1
	global_store_dwordx4 v1, v[4:7], s[4:5] offset:3328 sc0 sc1
	global_store_dwordx4 v1, v[4:7], s[4:5] offset:3392 sc0 sc1
	global_store_dwordx4 v1, v[4:7], s[4:5] offset:3456 sc0 sc1
	global_store_dwordx4 v1, v[4:7], s[4:5] offset:3520 sc0 sc1
	global_store_dwordx4 v1, v[4:7], s[4:5] offset:3584 sc0 sc1
	global_store_dwordx4 v1, v[4:7], s[4:5] offset:3648 sc0 sc1
	global_store_dwordx4 v1, v[4:7], s[4:5] offset:3712 sc0 sc1
	global_store_dwordx4 v1, v[4:7], s[4:5] offset:3776 sc0 sc1
	global_store_dwordx4 v1, v[4:7], s[4:5] offset:3840 sc0 sc1
	global_store_dwordx4 v1, v[4:7], s[4:5] offset:3904 sc0 sc1
	global_store_dwordx4 v1, v[4:7], s[4:5] offset:3968 sc0 sc1
	global_store_dwordx4 v1, v[4:7], s[4:5] offset:4032 sc0 sc1
	v_mov_b32_e32 v2, 0x7d00000
	v_mov_b32_e32 v3, 0x7d01000
	global_store_dword v2, v1, s[82:83] offset:0 sc0 sc1
	global_store_dword v2, v1, s[82:83] offset:128 sc0 sc1
	global_store_dword v2, v1, s[82:83] offset:256 sc0 sc1
	global_store_dword v2, v1, s[82:83] offset:384 sc0 sc1
	global_store_dword v2, v1, s[82:83] offset:512 sc0 sc1
	global_store_dword v2, v1, s[82:83] offset:640 sc0 sc1
	global_store_dword v2, v1, s[82:83] offset:768 sc0 sc1
	global_store_dword v2, v1, s[82:83] offset:896 sc0 sc1
	global_store_dword v2, v1, s[82:83] offset:1024 sc0 sc1
	global_store_dword v2, v1, s[82:83] offset:1152 sc0 sc1
	global_store_dword v2, v1, s[82:83] offset:1280 sc0 sc1
	global_store_dword v2, v1, s[82:83] offset:1408 sc0 sc1
	global_store_dword v2, v1, s[82:83] offset:1536 sc0 sc1
	global_store_dword v2, v1, s[82:83] offset:1664 sc0 sc1
	global_store_dword v2, v1, s[82:83] offset:1792 sc0 sc1
	global_store_dword v2, v1, s[82:83] offset:1920 sc0 sc1
	global_store_dword v2, v1, s[82:83] offset:2048 sc0 sc1
	global_store_dword v2, v1, s[82:83] offset:2176 sc0 sc1
	global_store_dword v2, v1, s[82:83] offset:2304 sc0 sc1
	global_store_dword v2, v1, s[82:83] offset:2432 sc0 sc1
	global_store_dword v2, v1, s[82:83] offset:2560 sc0 sc1
	global_store_dword v2, v1, s[82:83] offset:2688 sc0 sc1
	global_store_dword v2, v1, s[82:83] offset:2816 sc0 sc1
	global_store_dword v2, v1, s[82:83] offset:2944 sc0 sc1
	global_store_dword v2, v1, s[82:83] offset:3072 sc0 sc1
	global_store_dword v2, v1, s[82:83] offset:3200 sc0 sc1
	global_store_dword v2, v1, s[82:83] offset:3328 sc0 sc1
	global_store_dword v2, v1, s[82:83] offset:3456 sc0 sc1
	global_store_dword v2, v1, s[82:83] offset:3584 sc0 sc1
	global_store_dword v2, v1, s[82:83] offset:3712 sc0 sc1
	global_store_dword v2, v1, s[82:83] offset:3840 sc0 sc1
	global_store_dword v2, v1, s[82:83] offset:3968 sc0 sc1
	global_store_dword v3, v1, s[82:83] offset:0 sc0 sc1
	global_store_dword v3, v1, s[82:83] offset:128 sc0 sc1
	global_store_dword v3, v1, s[82:83] offset:256 sc0 sc1
	global_store_dword v3, v1, s[82:83] offset:384 sc0 sc1
	global_store_dword v3, v1, s[82:83] offset:512 sc0 sc1
	global_store_dword v3, v1, s[82:83] offset:640 sc0 sc1
	global_store_dword v3, v1, s[82:83] offset:768 sc0 sc1
	global_store_dword v3, v1, s[82:83] offset:896 sc0 sc1
	global_store_dword v3, v1, s[82:83] offset:1024 sc0 sc1
	global_store_dword v3, v1, s[82:83] offset:1152 sc0 sc1
	global_store_dword v3, v1, s[82:83] offset:1280 sc0 sc1
	global_store_dword v3, v1, s[82:83] offset:1408 sc0 sc1
	global_store_dword v3, v1, s[82:83] offset:1536 sc0 sc1
	global_store_dword v3, v1, s[82:83] offset:1664 sc0 sc1
	global_store_dword v3, v1, s[82:83] offset:1792 sc0 sc1
	global_store_dword v3, v1, s[82:83] offset:1920 sc0 sc1
	global_store_dword v3, v1, s[82:83] offset:2048 sc0 sc1
	global_store_dword v3, v1, s[82:83] offset:2176 sc0 sc1
	global_store_dword v3, v1, s[82:83] offset:2304 sc0 sc1
	global_store_dword v3, v1, s[82:83] offset:2432 sc0 sc1
	global_store_dword v3, v1, s[82:83] offset:2560 sc0 sc1
	global_store_dword v3, v1, s[82:83] offset:2688 sc0 sc1
	global_store_dword v3, v1, s[82:83] offset:2816 sc0 sc1
	global_store_dword v3, v1, s[82:83] offset:2944 sc0 sc1
	global_store_dword v3, v1, s[82:83] offset:3072 sc0 sc1
	global_store_dword v3, v1, s[82:83] offset:3200 sc0 sc1
	global_store_dword v3, v1, s[82:83] offset:3328 sc0 sc1
	global_store_dword v3, v1, s[82:83] offset:3456 sc0 sc1
	global_store_dword v3, v1, s[82:83] offset:3584 sc0 sc1
	global_store_dword v3, v1, s[82:83] offset:3712 sc0 sc1
	global_store_dword v3, v1, s[82:83] offset:3840 sc0 sc1
	global_store_dword v3, v1, s[82:83] offset:3968 sc0 sc1
	s_waitcnt vmcnt(0) lgkmcnt(0)
	v_mov_b32_e32 v2, 1
	global_atomic_add v1, v2, s[100:101] offset:32

; __global__ void __launch_bounds__(512, 2) hymba_fwd(Params p) {
;     ...
;         { pg8::Unit u0; for (int i = 0; S.next(i, u0); ++i) groupnorm_rows(p, u0.pm * 256, u0.pm * 256 + 256); }
;         asm volatile("s_waitcnt vmcnt(0)" ::: "memory");
;         __syncthreads();
.LBB0_400:
	s_waitcnt vmcnt(0)
	s_waitcnt vmcnt(3)
	v_mov_b32_e32 v8, v132
	v_cndmask_b32_e64 v0, 0, 1, s[76:77]
	s_waitcnt lgkmcnt(0)
	s_barrier
	s_cmpk_lg_i32 s33, 0x100
	s_cbranch_scc1 .Lgn_nosync
	v_cmp_eq_u32_e32 vcc, 0, v132
	s_and_saveexec_b64 s[100:101], vcc
	s_cbranch_execz .Lgn_sync_end
	s_lshl_b32 s97, s20, 7
	s_add_i32 s97, s97, 0x7d00000
	v_mov_b32_e32 v2, s97
	v_mov_b32_e32 v3, 1
	s_waitcnt vmcnt(0)
	global_atomic_add v2, v3, s[82:83]
	v_mov_b32_e32 v4, 0x1b71a80
	global_atomic_add v4, v3, s[82:83]

; template <int MODE>
; __device__ __forceinline__ void skinny(const Params& p, const h16* A, int lda, int row0, int nrt, const h16* Bt, int K, int nct) {
;     const int lane = threadIdx.x & 63, wave = threadIdx.x >> 6, fr = lane & 15, fq = lane >> 4;
;     const int gw = blockIdx.x * 8 + wave, ngw = gridDim.x * 8;
;     unsigned char* ws = p.ws;
;     for (int task = gw; task < nrt * nct; task += ngw) {
; __global__ void __launch_bounds__(512, 2) hymba_fwd(Params p) {
;     ...
;         pg8::gemm_phase(lds, g, S, E);
;         skinny<SK_OUT>(p, MIX, D, MP, MS / 16, (const h16*)(ws + OFF_WT_OUT), D, D / 16);
.LBB0_442:
	s_cmpk_lg_i32 s33, 0x100
	s_cbranch_scc1 .Lps_a1_end
	v_cmp_eq_u32_e32 vcc, 0, v132
	s_and_saveexec_b64 s[100:101], vcc
	s_cbranch_execz .Lps_a1_x
	s_and_b32 s97, s2, 63
	s_lshl_b32 s97, s97, 6
	s_add_i32 s97, s97, 0x1b6e900
	v_mov_b32_e32 v4, s97
	v_mov_b32_e32 v5, 1
	global_atomic_add v4, v5, s[82:83]
.Lps_a1_x:
	s_or_b64 exec, exec, s[100:101]
.Lps_a1_end:
	s_movk_i32 s0, 0x200
	v_or_b32_e32 v137, 0x4000, v131
	v_and_b32_e32 v16, 7, v130
	v_lshrrev_b32_e32 v17, 3, v130
	v_lshl_add_u32 v17, v17, 1, v16
	v_cmp_gt_u32_e32 vcc, 2, v16
	s_cmpk_eq_i32 s33, 0x100
	s_cselect_b64 s[98:99], -1, 0
	v_mov_b32_e32 v18, 0x7fff0000
	v_cndmask_b32_e32 v16, v18, v17, vcc
	v_cndmask_b32_e64 v16, v130, v16, s[98:99]
	v_cmp_gt_i32_e32 vcc, s0, v16
	s_and_saveexec_b64 s[0:1], vcc
	s_cbranch_execz .LBB0_449
	v_xor_b32_e32 v0, 16, v129
	v_cmp_lt_i32_e32 vcc, v0, v135
	v_mov_b32_e32 v5, 0
	v_cmp_eq_u32_e64 s[6:7], 0, v144
	v_cndmask_b32_e32 v0, v129, v0, vcc
	s_waitcnt vmcnt(2)
	v_lshlrev_b32_e32 v12, 2, v0
	v_xor_b32_e32 v0, 32, v129
	v_cmp_lt_i32_e32 vcc, v0, v135
	v_mov_b32_e32 v141, v5
	s_mov_b64 s[8:9], 0
	v_cndmask_b32_e32 v0, v129, v0, vcc
	v_lshlrev_b32_e32 v13, 2, v0
	s_mov_b64 s[12:13], 0x200
	s_movk_i32 s18, 0x1ff
	v_mov_b32_e32 v14, v16
	s_branch .LBB0_445

; __device__ __forceinline__ unsigned xb_ld(unsigned* p) { return __hip_atomic_load(p, __ATOMIC_RELAXED, __HIP_MEMORY_SCOPE_AGENT); }
; __device__ __forceinline__ unsigned xb_add(unsigned* p, unsigned v) { return __hip_atomic_fetch_add(p, v, __ATOMIC_RELAXED, __HIP_MEMORY_SCOPE_AGENT); }
; __device__ __forceinline__ void xcd_barrier(const XB& b) {
;     __syncthreads();
;     if (threadIdx.x == 0) {
;         unsigned* bar = b.bar;
;         __builtin_amdgcn_fence(__ATOMIC_RELEASE, "agent");
;         asm volatile("s_waitcnt vmcnt(0)" ::: "memory");
;         const unsigned old = xb_add(&bar[XB_XSUB(b.x)], 1u);
;         const unsigned gen = old / b.nloc;
;         if (old + 1u == (gen + 1u) * b.nloc) {
;             const unsigned og = xb_add(&bar[XB_TOP], 1u);
;             const unsigned target = (og / b.nx + 1u) * b.nx;
;             if (og + 1u != target) while (xb_ld(&bar[XB_TOP]) < target) __builtin_amdgcn_s_sleep(1);
;             xb_add(&bar[XB_XGEN(b.x)], 1u);
;         } else {
;             while (xb_ld(&bar[XB_XGEN(b.x)]) == gen) __builtin_amdgcn_s_sleep(1);
;         }
;         __builtin_amdgcn_fence(__ATOMIC_ACQUIRE, "agent");
;         asm volatile("s_waitcnt vmcnt(0)" ::: "memory");
;     }
;     __syncthreads();
.Linvw_2:
	s_mov_b64 s[0:1], exec
	v_readlane_b32 s6, v253, 2
	v_readlane_b32 s7, v253, 3
	s_and_b64 s[6:7], s[0:1], s[6:7]
	s_mov_b64 exec, s[6:7]
	s_cbranch_execz .LBB0_468
	s_cmpk_lg_i32 s33, 0x100
	s_cbranch_scc1 .Lps_a2_orig
	v_mov_b32_e32 v4, 0x1b71980
	v_mov_b32_e32 v5, 1
	global_atomic_add v4, v5, s[82:83]
	s_and_b32 s97, s2, 63
	s_lshl_b32 s97, s97, 6
	s_add_i32 s97, s97, 0x1b6e900
	v_mov_b32_e32 v4, s97
	v_mov_b32_e32 v5, 0x1b71a80
.Lps_a2_poll:
	global_load_dword v6, v4, s[82:83] sc1
	global_load_dword v7, v5, s[82:83] sc1
	s_waitcnt vmcnt(0)
	v_readfirstlane_b32 s97, v6
	v_readfirstlane_b32 s98, v7
	s_cmp_lt_u32 s97, 4
	s_cbranch_scc1 .Lps_a2_slp
	s_cmpk_lt_u32 s98, 0x100
	s_cbranch_scc0 .LBB0_468
.Lps_a2_slp:
	s_sleep 1
	s_branch .Lps_a2_poll
.Lps_a2_orig:
	s_mov_b64 s[8:9], exec
	s_nop 0
	s_waitcnt vmcnt(0)
	s_waitcnt vmcnt(0)
	s_lshl_b32 s6, s89, 8
	v_readlane_b32 s12, v253, 0
	v_mbcnt_lo_u32_b32 v0, s8, 0
	v_readlane_b32 s13, v253, 1
	s_add_u32 s6, s12, s6
	v_mbcnt_hi_u32_b32 v0, s9, v0
	s_addc_u32 s7, s13, 0
	v_cmp_eq_u32_e32 vcc, 0, v0
	s_and_saveexec_b64 s[12:13], vcc
	s_cbranch_execz .LBB0_452
	s_bcnt1_i32_b64 s8, s[8:9]
	v_mov_b32_e32 v1, 0x1000
	v_mov_b32_e32 v2, s8
	global_atomic_add v1, v1, v2, s[6:7] sc0

; __global__ void __launch_bounds__(512, 2) hymba_fwd(Params p) {
;     ...
;         pg8::gemm_phase(lds, g, S, E);
;         skinny<SK_UP>(p, (const h16*)(ws + OFF_X116), D, MP, MS / 16, (const h16*)(ws + OFF_WT_UP), D, DFF / 16);
.LBB0_487:
	v_mov_b32_e32 v218, 0x1b71980
	global_load_dword v219, v218, s[82:83] sc1
	v_readlane_b32 s48, v253, 20
	v_readlane_b32 s60, v253, 32
	v_readlane_b32 s61, v253, 33
	v_readlane_b32 s62, v253, 34
	v_readlane_b32 s63, v253, 35
	s_barrier
	v_readlane_b32 s49, v253, 21
	v_readlane_b32 s50, v253, 22
	v_readlane_b32 s51, v253, 23
	v_readlane_b32 s52, v253, 24
	v_readlane_b32 s53, v253, 25
	v_readlane_b32 s54, v253, 26
	v_readlane_b32 s55, v253, 27
	v_readlane_b32 s56, v253, 28
	v_readlane_b32 s57, v253, 29
	v_readlane_b32 s58, v253, 30
	v_readlane_b32 s59, v253, 31

; __device__ __forceinline__ f32x4 mfma16(h16x8 a, h16x8 b, f32x4 c) { return __builtin_amdgcn_mfma_f32_16x16x32_f16(a, b, c, 0, 0, 0); }
; template <int MODE>
; __device__ __forceinline__ void skinny(const Params& p, const h16* A, int lda, int row0, int nrt, const h16* Bt, int K, int nct) {
;     const int lane = threadIdx.x & 63, wave = threadIdx.x >> 6, fr = lane & 15, fq = lane >> 4;
;     const int gw = blockIdx.x * 8 + wave, ngw = gridDim.x * 8;
;     unsigned char* ws = p.ws;
;     for (int task = gw; task < nrt * nct; task += ngw) {
;         const int rt = task % nrt, ct = task / nrt;
;         const h16* ap = A + (size_t)(row0 + rt * 16 + fr) * lda + fq * 8;
;         const h16* bp = Bt + (size_t)(ct * 16 + fr) * K + fq * 8;
;         f32x4 acc = {0.f, 0.f, 0.f, 0.f};
; #pragma unroll 8
;         for (int k = 0; k < K; k += 32) { const h16x8 a = *(const h16x8*)(ap + k); const h16x8 b = *(const h16x8*)(bp + k); acc = mfma16(b, a, acc); }
.LBB0_491:
	s_cmpk_lg_i32 s33, 0x100
	s_cbranch_scc1 .Lsk5_orig
	s_waitcnt vmcnt(0)
.Lps_u_chk:
	v_readfirstlane_b32 s100, v219
	s_cmpk_lt_u32 s100, 0x100
	s_cbranch_scc0 .Lps_u_ok
	s_sleep 1
	global_load_dword v219, v218, s[82:83] sc1
	s_waitcnt vmcnt(0)
	s_branch .Lps_u_chk
.Lps_u_ok:
	v_lshrrev_b32_e32 v24, 6, v132
	v_and_b32_e32 v200, 63, v132
	v_readfirstlane_b32 s97, v24
	v_lshlrev_b32_e32 v200, 4, v200
	v_lshl_add_u64 v[24:25], v[8:9], 0, v[140:141]
	v_lshl_add_u64 v[26:27], v[6:7], 0, v[140:141]
	s_lshl_b32 s98, s97, 8
	s_lshl_b32 s99, s97, 12
	s_add_u32 s98, s98, 0x988000
	v_add_co_u32_e32 v24, vcc, s98, v24
	s_nop 1
	v_addc_co_u32_e32 v25, vcc, 0, v25, vcc
	v_add_co_u32_e32 v26, vcc, 0x5c72900, v26
	s_nop 1
	v_addc_co_u32_e32 v27, vcc, 0, v27, vcc
	s_add_i32 m0, s99, 0x0
	s_nop 0
	global_load_lds_dwordx4 v[24:25], off
	v_add_co_u32_e32 v24, vcc, 64, v24
	s_nop 1
	v_addc_co_u32_e32 v25, vcc, 0, v25, vcc
	s_add_i32 m0, s99, 0x400
	s_nop 0
	global_load_lds_dwordx4 v[24:25], off
	v_add_co_u32_e32 v24, vcc, 64, v24
	s_nop 1
	v_addc_co_u32_e32 v25, vcc, 0, v25, vcc
	s_add_i32 m0, s99, 0x800
	s_nop 0
	global_load_lds_dwordx4 v[24:25], off
	v_add_co_u32_e32 v24, vcc, 64, v24
	s_nop 1
	v_addc_co_u32_e32 v25, vcc, 0, v25, vcc
	s_add_i32 m0, s99, 0xc00
	s_nop 0
	global_load_lds_dwordx4 v[24:25], off
	global_load_dwordx4 v[28:31], v[26:27], off
	global_load_dwordx4 v[32:35], v[26:27], off offset:64
	global_load_dwordx4 v[36:39], v[26:27], off offset:128
	global_load_dwordx4 v[40:43], v[26:27], off offset:192
	global_load_dwordx4 v[44:47], v[26:27], off offset:256
	global_load_dwordx4 v[48:51], v[26:27], off offset:320
	global_load_dwordx4 v[52:55], v[26:27], off offset:384
	global_load_dwordx4 v[56:59], v[26:27], off offset:448
	global_load_dwordx4 v[60:63], v[26:27], off offset:512
	global_load_dwordx4 v[64:67], v[26:27], off offset:576
	global_load_dwordx4 v[68:71], v[26:27], off offset:640
	global_load_dwordx4 v[72:75], v[26:27], off offset:704
	global_load_dwordx4 v[76:79], v[26:27], off offset:768
	global_load_dwordx4 v[80:83], v[26:27], off offset:832
	global_load_dwordx4 v[84:87], v[26:27], off offset:896
	global_load_dwordx4 v[88:91], v[26:27], off offset:960
	global_load_dwordx4 v[92:95], v[26:27], off offset:1024
	global_load_dwordx4 v[96:99], v[26:27], off offset:1088
	global_load_dwordx4 v[100:103], v[26:27], off offset:1152
	global_load_dwordx4 v[104:107], v[26:27], off offset:1216
	global_load_dwordx4 v[108:111], v[26:27], off offset:1280
	global_load_dwordx4 v[112:115], v[26:27], off offset:1344
	global_load_dwordx4 v[116:119], v[26:27], off offset:1408
	global_load_dwordx4 v[120:123], v[26:27], off offset:1472
	global_load_dwordx4 v[124:127], v[26:27], off offset:1536
	global_load_dwordx4 v[148:151], v[26:27], off offset:1600
	global_load_dwordx4 v[152:155], v[26:27], off offset:1664
	global_load_dwordx4 v[156:159], v[26:27], off offset:1728
	global_load_dwordx4 v[160:163], v[26:27], off offset:1792
	global_load_dwordx4 v[164:167], v[26:27], off offset:1856
	global_load_dwordx4 v[168:171], v[26:27], off offset:1920
	global_load_dwordx4 v[172:175], v[26:27], off offset:1984
	s_waitcnt vmcnt(32)
	s_barrier
; __device__ __forceinline__ f32x4 mfma16(h16x8 a, h16x8 b, f32x4 c) { return __builtin_amdgcn_mfma_f32_16x16x32_f16(a, b, c, 0, 0, 0); }
; template <int MODE>
; __device__ __forceinline__ void skinny(const Params& p, const h16* A, int lda, int row0, int nrt, const h16* Bt, int K, int nct) {
;     const int lane = threadIdx.x & 63, wave = threadIdx.x >> 6, fr = lane & 15, fq = lane >> 4;
;     const int gw = blockIdx.x * 8 + wave, ngw = gridDim.x * 8;
;     unsigned char* ws = p.ws;
;     for (int task = gw; task < nrt * nct; task += ngw) {
;         const int rt = task % nrt, ct = task / nrt;
;         const h16* ap = A + (size_t)(row0 + rt * 16 + fr) * lda + fq * 8;
;         const h16* bp = Bt + (size_t)(ct * 16 + fr) * K + fq * 8;
;         f32x4 acc = {0.f, 0.f, 0.f, 0.f};
; #pragma unroll 8
;         for (int k = 0; k < K; k += 32) { const h16x8 a = *(const h16x8*)(ap + k); const h16x8 b = *(const h16x8*)(bp + k); acc = mfma16(b, a, acc); }
	ds_read_b128 v[176:179], v200
	ds_read_b128 v[180:183], v200 offset:1024
	ds_read_b128 v[184:187], v200 offset:2048
	ds_read_b128 v[188:191], v200 offset:3072
	s_waitcnt vmcnt(31) lgkmcnt(3)
	v_mfma_f32_16x16x32_f16 v[0:3], v[176:179], v[28:31], v[0:3]
	ds_read_b128 v[192:195], v200 offset:4096
	s_waitcnt vmcnt(30) lgkmcnt(3)
	v_mfma_f32_16x16x32_f16 v[0:3], v[180:183], v[32:35], v[0:3]
	ds_read_b128 v[196:199], v200 offset:5120
	s_waitcnt vmcnt(29) lgkmcnt(3)
	v_mfma_f32_16x16x32_f16 v[0:3], v[184:187], v[36:39], v[0:3]
	ds_read_b128 v[176:179], v200 offset:6144
	s_waitcnt vmcnt(28) lgkmcnt(3)
	v_mfma_f32_16x16x32_f16 v[0:3], v[188:191], v[40:43], v[0:3]
	ds_read_b128 v[180:183], v200 offset:7168
	s_waitcnt vmcnt(27) lgkmcnt(3)
	v_mfma_f32_16x16x32_f16 v[0:3], v[192:195], v[44:47], v[0:3]
	ds_read_b128 v[184:187], v200 offset:8192
	s_waitcnt vmcnt(26) lgkmcnt(3)
	v_mfma_f32_16x16x32_f16 v[0:3], v[196:199], v[48:51], v[0:3]
	ds_read_b128 v[188:191], v200 offset:9216
	s_waitcnt vmcnt(25) lgkmcnt(3)
	v_mfma_f32_16x16x32_f16 v[0:3], v[176:179], v[52:55], v[0:3]
	ds_read_b128 v[192:195], v200 offset:10240
	s_waitcnt vmcnt(24) lgkmcnt(3)
	v_mfma_f32_16x16x32_f16 v[0:3], v[180:183], v[56:59], v[0:3]
	ds_read_b128 v[196:199], v200 offset:11264
	s_waitcnt vmcnt(23) lgkmcnt(3)
	v_mfma_f32_16x16x32_f16 v[0:3], v[184:187], v[60:63], v[0:3]
	ds_read_b128 v[176:179], v200 offset:12288
	s_waitcnt vmcnt(22) lgkmcnt(3)
	v_mfma_f32_16x16x32_f16 v[0:3], v[188:191], v[64:67], v[0:3]
	ds_read_b128 v[180:183], v200 offset:13312
	s_waitcnt vmcnt(21) lgkmcnt(3)
	v_mfma_f32_16x16x32_f16 v[0:3], v[192:195], v[68:71], v[0:3]
	ds_read_b128 v[184:187], v200 offset:14336
	s_waitcnt vmcnt(20) lgkmcnt(3)
	v_mfma_f32_16x16x32_f16 v[0:3], v[196:199], v[72:75], v[0:3]
	ds_read_b128 v[188:191], v200 offset:15360
	s_waitcnt vmcnt(19) lgkmcnt(3)
	v_mfma_f32_16x16x32_f16 v[0:3], v[176:179], v[76:79], v[0:3]
	ds_read_b128 v[192:195], v200 offset:16384
	s_waitcnt vmcnt(18) lgkmcnt(3)
	v_mfma_f32_16x16x32_f16 v[0:3], v[180:183], v[80:83], v[0:3]
	ds_read_b128 v[196:199], v200 offset:17408
	s_waitcnt vmcnt(17) lgkmcnt(3)
	v_mfma_f32_16x16x32_f16 v[0:3], v[184:187], v[84:87], v[0:3]
	ds_read_b128 v[176:179], v200 offset:18432
	s_waitcnt vmcnt(16) lgkmcnt(3)
	v_mfma_f32_16x16x32_f16 v[0:3], v[188:191], v[88:91], v[0:3]
	ds_read_b128 v[180:183], v200 offset:19456
	s_waitcnt vmcnt(15) lgkmcnt(3)
	v_mfma_f32_16x16x32_f16 v[0:3], v[192:195], v[92:95], v[0:3]
	ds_read_b128 v[184:187], v200 offset:20480
	s_waitcnt vmcnt(14) lgkmcnt(3)
	v_mfma_f32_16x16x32_f16 v[0:3], v[196:199], v[96:99], v[0:3]
	ds_read_b128 v[188:191], v200 offset:21504
	s_waitcnt vmcnt(13) lgkmcnt(3)
	v_mfma_f32_16x16x32_f16 v[0:3], v[176:179], v[100:103], v[0:3]
	ds_read_b128 v[192:195], v200 offset:22528
	s_waitcnt vmcnt(12) lgkmcnt(3)
	v_mfma_f32_16x16x32_f16 v[0:3], v[180:183], v[104:107], v[0:3]
	ds_read_b128 v[196:199], v200 offset:23552
	s_waitcnt vmcnt(11) lgkmcnt(3)
	v_mfma_f32_16x16x32_f16 v[0:3], v[184:187], v[108:111], v[0:3]
	ds_read_b128 v[176:179], v200 offset:24576
	s_waitcnt vmcnt(10) lgkmcnt(3)
	v_mfma_f32_16x16x32_f16 v[0:3], v[188:191], v[112:115], v[0:3]
	ds_read_b128 v[180:183], v200 offset:25600
	s_waitcnt vmcnt(9) lgkmcnt(3)
	v_mfma_f32_16x16x32_f16 v[0:3], v[192:195], v[116:119], v[0:3]
	ds_read_b128 v[184:187], v200 offset:26624
	s_waitcnt vmcnt(8) lgkmcnt(3)
	v_mfma_f32_16x16x32_f16 v[0:3], v[196:199], v[120:123], v[0:3]
	ds_read_b128 v[188:191], v200 offset:27648
	s_waitcnt vmcnt(7) lgkmcnt(3)
	v_mfma_f32_16x16x32_f16 v[0:3], v[176:179], v[124:127], v[0:3]
	ds_read_b128 v[192:195], v200 offset:28672
	s_waitcnt vmcnt(6) lgkmcnt(3)
	v_mfma_f32_16x16x32_f16 v[0:3], v[180:183], v[148:151], v[0:3]
	ds_read_b128 v[196:199], v200 offset:29696
	s_waitcnt vmcnt(5) lgkmcnt(3)
	v_mfma_f32_16x16x32_f16 v[0:3], v[184:187], v[152:155], v[0:3]
	ds_read_b128 v[176:179], v200 offset:30720
	s_waitcnt vmcnt(4) lgkmcnt(3)
	v_mfma_f32_16x16x32_f16 v[0:3], v[188:191], v[156:159], v[0:3]
	ds_read_b128 v[180:183], v200 offset:31744
	s_waitcnt vmcnt(3) lgkmcnt(3)
	v_mfma_f32_16x16x32_f16 v[0:3], v[192:195], v[160:163], v[0:3]
	s_waitcnt vmcnt(2) lgkmcnt(2)
	v_mfma_f32_16x16x32_f16 v[0:3], v[196:199], v[164:167], v[0:3]
	s_waitcnt vmcnt(1) lgkmcnt(1)
	v_mfma_f32_16x16x32_f16 v[0:3], v[176:179], v[168:171], v[0:3]
	s_waitcnt vmcnt(0) lgkmcnt(0)
	v_mfma_f32_16x16x32_f16 v[0:3], v[180:183], v[172:175], v[0:3]
	s_branch .Lsk5_done
